# odd teams run (out-proj,norm2) and (down,next norm) panel by panel: their bandwidth-bound norm halves fall into the other teams' GEMM time; same work, different order
# speedup vs baseline: 1.0175x; 1.0090x over previous
.LBB0_5:
	s_or_b64 exec, exec, s[2:3]
	s_cmp_ge_i32 s80, s81
	s_cbranch_scc1 .LBB0_487
	s_add_u32 s4, s78, 0x17024800
	s_addc_u32 s5, s79, 0
	s_add_u32 s2, s78, 0x36000
	s_addc_u32 s3, s79, 0
	s_add_u32 s8, s78, 0x3824800
	v_writelane_b32 v253, s2, 2
	s_addc_u32 s9, s79, 0
	s_movk_i32 s82, 0x161
	v_writelane_b32 v253, s3, 3
	s_add_u32 s2, s78, 0x39000
	s_addc_u32 s3, s79, 0
	s_lshl_b32 s61, s62, 3
	s_mov_b32 s100, 0
	v_writelane_b32 v255, s100, 47
	v_writelane_b32 v255, s100, 48
	s_add_u32 s38, s0, 0x88
	s_addc_u32 s39, s1, 0
	s_add_u32 s58, s78, 0x4000
	s_addc_u32 s59, s79, 0
	v_writelane_b32 v253, s2, 4
	s_cmpk_lt_i32 s62, 0xc0
	v_lshrrev_b32_e32 v1, 20, v0
	v_writelane_b32 v253, s3, 5
	s_cselect_b64 s[2:3], -1, 0
	v_writelane_b32 v253, s2, 6
	s_cmp_eq_u32 s62, 0
	v_lshrrev_b32_e32 v0, 10, v0
	v_writelane_b32 v253, s3, 7
	s_cselect_b64 s[2:3], -1, 0
	v_writelane_b32 v253, s2, 8
	v_or_b32_e32 v0, v0, v1
	s_load_dwordx16 s[40:55], s[0:1], 0x0
	v_writelane_b32 v253, s3, 9
	s_add_u32 s2, s78, 0x64000
	s_addc_u32 s3, s79, 0
	s_add_u32 s22, s78, 0x7824800
	v_writelane_b32 v253, s2, 10
	s_addc_u32 s23, s79, 0
	s_mov_b32 s97, 0
	v_writelane_b32 v253, s3, 11
	s_add_u32 s2, s78, 0x2d24800
	s_addc_u32 s3, s79, 0
	v_writelane_b32 v253, s2, 12
	s_cmpk_lt_i32 s62, 0x200
	v_mbcnt_lo_u32_b32 v1, -1, 0
	v_writelane_b32 v253, s3, 13
	s_cselect_b64 s[2:3], -1, 0
	v_writelane_b32 v253, s2, 14
	s_ashr_i32 s63, s62, 31
	s_mov_b32 s98, s97
	v_writelane_b32 v253, s3, 15
	s_lshr_b32 s2, s63, 29
	s_add_i32 s3, s62, s2
	s_ashr_i32 s2, s3, 3
	s_and_b32 s3, s3, -8
	s_sub_i32 s3, s62, s3
	s_lshl_b32 s7, s3, 6
	s_add_u32 s10, s78, 0x1724800
	s_addc_u32 s11, s79, 0
	v_writelane_b32 v253, s10, 16
	s_cmpk_lt_i32 s62, 0xb00
	s_mov_b32 s99, s97
	v_writelane_b32 v253, s11, 17
	s_cselect_b64 s[10:11], -1, 0
	v_writelane_b32 v253, s10, 18
	v_mbcnt_hi_u32_b32 v204, -1, v1
	s_mov_b32 s96, s97
	v_writelane_b32 v253, s11, 19
	s_lshl_b32 s10, s3, 8
	s_cmp_lt_i32 s3, 0
	s_cselect_b32 s12, s82, 0x160
	s_mul_i32 s11, s3, 0x41
	s_mul_i32 s12, s12, s3
	s_mulk_i32 s3, 0x101
	s_cselect_b32 s7, s11, s7
	s_cselect_b32 s3, s3, s10
	s_add_i32 s12, s12, s2
	s_mul_hi_i32 s10, s12, 0x2e8ba2e9
	s_lshr_b32 s11, s10, 31
	s_ashr_i32 s10, s10, 5
	s_add_i32 s10, s10, s11
	s_mul_i32 s11, s10, 0xb0
	s_sub_i32 s11, s12, s11
	s_lshl_b32 s13, s10, 3
	s_bfe_u32 s10, s11, 0x3001c
	s_add_i32 s12, s11, s10
	s_sext_i32_i16 s14, s12
	s_and_b32 s12, s12, 0xfff8
	s_sub_i32 s11, s11, s12
	s_sext_i32_i16 s11, s11
	s_ashr_i32 s12, s14, 3
	s_add_i32 s11, s13, s11
	v_writelane_b32 v253, s12, 20
	s_lshr_b32 s10, s14, 3
	v_writelane_b32 v253, s11, 21
	s_ashr_i32 s11, s11, 31
	v_writelane_b32 v253, s11, 22
	s_bfe_i64 s[10:11], s[10:11], 0x100000
	v_writelane_b32 v253, s10, 23
	v_mov_b64_e32 v[242:243], s[98:99]
	v_and_b32_e32 v1, 64, v204
	v_writelane_b32 v253, s11, 24
	s_add_u32 s10, s78, 0x1324800
	s_addc_u32 s11, s79, 0
	v_writelane_b32 v253, s10, 25
	s_cmpk_lt_i32 s62, 0x600
	v_mov_b32_e32 v129, 0
	v_writelane_b32 v253, s11, 26
	s_cselect_b64 s[10:11], -1, 0
	v_writelane_b32 v253, s10, 27
	v_mov_b32_e32 v201, 0x358637bd
	v_mov_b32_e32 v202, 0x3ecc95a3
	v_writelane_b32 v253, s11, 28
	s_ashr_i32 s10, s62, 5
	s_mul_hi_i32 s11, s10, 0x2aaaaaab
	s_lshr_b32 s12, s11, 31
	s_add_i32 s11, s11, s12
	s_mul_i32 s12, s11, 6
	s_sub_i32 s10, s10, s12
	s_lshl_b32 s12, s62, 7
	s_lshl_b32 s11, s11, 12
	v_writelane_b32 v253, s12, 29
	s_and_b32 s12, s12, 0xf80
	s_lshl_b32 s10, s10, 6
	s_or_b32 s88, s11, s12
	s_ashr_i32 s11, s10, 31
	s_lshl_b64 s[10:11], s[10:11], 1
	s_add_u32 s10, s22, s10
	s_addc_u32 s11, s23, s11
	v_writelane_b32 v253, s10, 30
	s_add_u32 s12, s78, 0x1b824800
	s_addc_u32 s13, s79, 0
	v_writelane_b32 v253, s11, 31
	s_lshl_b64 s[10:11], s[62:63], 14
	s_add_u32 s10, s12, s10
	v_writelane_b32 v253, s12, 32
	s_addc_u32 s11, s13, s11
	v_mov_b64_e32 v[240:241], s[96:97]
	v_writelane_b32 v253, s13, 33
	s_add_u32 s12, s10, 0x2000
	v_writelane_b32 v253, s10, 34
	s_addc_u32 s13, s11, 0
	s_cmpk_lt_i32 s62, 0x100
	v_writelane_b32 v253, s11, 35
	v_writelane_b32 v253, s12, 36
	s_cselect_b64 s[10:11], -1, 0
	v_mov_b32_e32 v203, 1
	v_writelane_b32 v253, s13, 37
	v_writelane_b32 v253, s10, 38
	v_add_u32_e32 v205, 64, v1
	v_xor_b32_e32 v206, 1, v204
	v_writelane_b32 v253, s11, 39
	s_add_u32 s10, s78, 0x1d024800
	s_addc_u32 s11, s79, 0
	v_writelane_b32 v253, s10, 40
	v_xor_b32_e32 v207, 2, v204
	v_xor_b32_e32 v252, 4, v204
	v_writelane_b32 v253, s11, 41
	s_add_u32 s10, s78, 0xe4800
	s_addc_u32 s11, s79, 0
	s_lshl_b32 s89, s62, 9
	s_add_u32 s30, s78, 0x64800
	s_addc_u32 s31, s79, 0
	s_add_i32 s91, s89, 0xffff4000
	s_add_i32 s12, s61, 0xd40
	v_writelane_b32 v253, s12, 42
	s_add_u32 s12, s78, 0x324800
	s_addc_u32 s13, s79, 0
	v_writelane_b32 v253, s12, 43
	v_xor_b32_e32 v210, 16, v204
	v_xor_b32_e32 v211, 32, v204
	v_writelane_b32 v253, s13, 44
	s_and_b32 s12, s62, 7
	s_xor_b32 s13, s12, 7
	s_cmpk_lt_u32 s62, 0x900
	v_writelane_b32 v253, s13, 45
	s_cselect_b64 s[14:15], -1, 0
	v_writelane_b32 v253, s14, 46
	s_lshl_b32 s92, s12, 6
	v_mov_b64_e32 v[130:131], 0x200
	v_writelane_b32 v253, s15, 47
	s_lshr_b32 s15, s62, 3
	s_mul_i32 s13, s15, 0xaaab
	s_lshr_b32 s13, s13, 21
	s_mul_i32 s14, s13, 0xffffffd0
	s_lshl_b32 s13, s13, 9
	s_add_i32 s14, s14, s15
	s_or_b32 s12, s13, s92
	s_or_b32 s12, s12, s14
	s_ashr_i32 s12, s12, 6
	s_lshr_b32 s14, s14, 3
	s_mul_hi_i32 s13, s12, 0x2aaaaaab
	s_and_b32 s17, s14, 6
	v_writelane_b32 v253, s15, 48
	s_lshr_b32 s15, s13, 31
	s_lshr_b32 s16, 16, s17
	s_add_i32 s13, s13, s15
	s_bfe_u32 s14, s62, 0x40003
	s_sub_i32 s15, 4, s17
	s_add_i32 s16, s16, -1
	s_lshr_b32 s15, s14, s15
	s_and_b32 s14, s16, s14
	s_lshl_b32 s16, s13, 12
	s_or_b32 s15, s16, s15
	s_mul_i32 s13, s13, 6
	v_writelane_b32 v253, s15, 49
	s_sub_i32 s12, s12, s13
	s_lshl_b32 s12, s12, 6
	v_writelane_b32 v253, s17, 50
	s_lshr_b32 s15, 0x1000, s17
	s_lshl_b32 s14, s14, 8
	s_ashr_i32 s13, s12, 31
	v_writelane_b32 v253, s15, 51
	s_lshl_b64 s[12:13], s[12:13], 1
	v_writelane_b32 v253, s14, 52
	s_sub_i32 s14, s14, 64
	s_add_u32 s12, s22, s12
	v_writelane_b32 v253, s14, 53
	s_addc_u32 s13, s23, s13
	v_writelane_b32 v253, s12, 54
	s_cmpk_lt_i32 s62, 0x400
	v_mov_b64_e32 v[132:133], 0x1ff
	v_writelane_b32 v253, s13, 55
	s_cselect_b64 s[12:13], -1, 0
	v_writelane_b32 v253, s12, 56
	s_cmpk_lt_i32 s62, 0x800
	v_mov_b32_e32 v212, 0x42800000
	v_writelane_b32 v253, s13, 57
	s_cselect_b64 s[12:13], -1, 0
	v_writelane_b32 v253, s12, 58
	s_cmp_lt_i32 s81, 21
	v_mov_b32_e32 v213, 0x7fc00000
	v_writelane_b32 v253, s13, 59
	s_cselect_b64 s[12:13], -1, 0
	v_writelane_b32 v253, s12, 60
	v_mov_b32_e32 v214, 0xff800000
	v_mov_b32_e32 v215, 0x41f00000
	v_writelane_b32 v253, s13, 61
	s_add_u32 s12, s78, 0x200
	s_addc_u32 s13, s79, 0
	v_writelane_b32 v253, s12, 62
	v_mov_b32_e32 v216, 0x1f00
	v_mov_b32_e32 v217, 6
	v_writelane_b32 v253, s13, 63
	s_add_u32 s12, s78, 0x1000
	s_addc_u32 s13, s79, 0
	v_writelane_b32 v254, s12, 0
	v_mov_b32_e32 v134, 0x3e38aa3b
	v_mov_b32_e32 v218, 0xf149f2ca
	v_writelane_b32 v254, s13, 1
	s_add_u32 s12, s78, 0x1100
	s_addc_u32 s13, s79, 0
	v_writelane_b32 v254, s12, 2
	v_mov_b32_e32 v136, 0x3f317218
	v_mov_b64_e32 v[138:139], 0x7ff
	v_writelane_b32 v254, s13, 3
	s_add_u32 s12, s78, 0x1200
	s_addc_u32 s13, s79, 0
	v_writelane_b32 v254, s12, 4
	v_mov_b32_e32 v219, 0x3f7fffef
	s_mov_b32 s95, 0x2aaaaaab
	v_writelane_b32 v254, s13, 5
	s_add_u32 s12, s78, 0x1300
	s_addc_u32 s13, s79, 0
	v_writelane_b32 v254, s12, 6
	s_cmp_eq_u32 s6, 15
	s_movk_i32 s94, 0xf80
	v_writelane_b32 v254, s13, 7
	s_cselect_b64 s[12:13], -1, 0
	v_writelane_b32 v254, s12, 8
	s_cmp_eq_u32 s6, 14
	s_movk_i32 s86, 0x1000
	v_writelane_b32 v254, s13, 9
	s_cselect_b64 s[12:13], -1, 0
	v_writelane_b32 v254, s12, 10
	s_cmp_eq_u32 s6, 13
	s_movk_i32 s84, 0x6000
	v_writelane_b32 v254, s13, 11
	s_cselect_b64 s[12:13], -1, 0
	v_writelane_b32 v254, s12, 12
	s_cmp_eq_u32 s6, 12
	s_mov_b32 s60, 0xec801000
	v_writelane_b32 v254, s13, 13
	s_cselect_b64 s[12:13], -1, 0
	v_writelane_b32 v254, s12, 14
	s_cmp_eq_u32 s6, 11
	s_mov_b32 s33, 0xc000
	v_writelane_b32 v254, s13, 15
	s_cselect_b64 s[12:13], -1, 0
	v_writelane_b32 v254, s12, 16
	s_cmp_eq_u32 s6, 10
	s_movk_i32 s93, 0x1f00
	v_writelane_b32 v254, s13, 17
	s_cselect_b64 s[12:13], -1, 0
	v_writelane_b32 v254, s12, 18
	s_cmp_eq_u32 s6, 9
	s_mov_b32 s85, 0xc1f00000
	v_writelane_b32 v254, s13, 19
	s_cselect_b64 s[12:13], -1, 0
	v_writelane_b32 v254, s12, 20
	s_cmp_eq_u32 s6, 8
	s_mov_b32 s90, 0xc0000
	v_writelane_b32 v254, s13, 21
	s_cselect_b64 s[12:13], -1, 0
	v_writelane_b32 v254, s12, 22
	s_cmp_eq_u32 s6, 7
	s_mov_b32 s87, 0x180000
	v_writelane_b32 v254, s13, 23
	s_cselect_b64 s[12:13], -1, 0
	v_writelane_b32 v254, s12, 24
	s_cmp_eq_u32 s6, 6
	s_movk_i32 s83, 0x300
	v_writelane_b32 v254, s13, 25
	s_cselect_b64 s[12:13], -1, 0
	v_writelane_b32 v254, s12, 26
	s_cmp_eq_u32 s6, 5
	s_mov_b64 s[98:99], 0x80
	v_writelane_b32 v254, s13, 27
	s_cselect_b64 s[12:13], -1, 0
	v_writelane_b32 v254, s12, 28
	s_cmp_eq_u32 s6, 4
	s_mov_b32 s18, 0x3e38aa3b
	v_writelane_b32 v254, s13, 29
	s_cselect_b64 s[12:13], -1, 0
	v_writelane_b32 v254, s12, 30
	s_cmp_eq_u32 s6, 3
	s_nop 0
	v_writelane_b32 v254, s13, 31
	s_cselect_b64 s[12:13], -1, 0
	v_writelane_b32 v254, s12, 32
	s_cmp_eq_u32 s6, 2
	s_nop 0
	v_writelane_b32 v254, s13, 33
	s_cselect_b64 s[12:13], -1, 0
	v_writelane_b32 v254, s12, 34
	s_cmp_eq_u32 s6, 1
	s_nop 0
	v_writelane_b32 v254, s13, 35
	s_cselect_b64 s[12:13], -1, 0
	v_writelane_b32 v254, s12, 36
	s_cmp_eq_u32 s6, 0
	s_nop 0
	v_writelane_b32 v254, s13, 37
	s_cselect_b64 s[12:13], -1, 0
	s_lshl_b32 s6, s6, 8
	v_writelane_b32 v254, s12, 38
	s_add_u32 s6, s78, s6
	s_nop 0
	v_writelane_b32 v254, s13, 39
	s_addc_u32 s12, s79, 0
	s_add_u32 s14, s6, 0x1400
	s_addc_u32 s15, s12, 0
	v_writelane_b32 v254, s14, 40
	s_nop 1
	v_writelane_b32 v254, s15, 41
	s_add_u32 s14, s6, 0x2400
	s_addc_u32 s15, s12, 0
	v_writelane_b32 v254, s14, 42
	s_add_u32 s12, s78, 0x3400
	s_addc_u32 s13, s79, 0
	v_writelane_b32 v254, s15, 43
	v_writelane_b32 v254, s12, 44
	s_nop 1
	v_writelane_b32 v254, s13, 45
	s_add_u32 s12, s78, 0x3500
	s_addc_u32 s13, s79, 0
	s_add_i32 s6, s7, s2
	s_ashr_i32 s7, s6, 31
	s_lshr_b32 s7, s7, 27
	v_writelane_b32 v254, s12, 46
	s_add_i32 s7, s6, s7
	s_add_i32 s2, s3, s2
	v_writelane_b32 v254, s13, 47
	s_and_b32 s12, s7, 0xffe0
	s_sub_i32 s6, s6, s12
	s_bfe_i32 s12, s6, 0x80000
	s_bfe_u32 s12, s12, 0x3000c
	s_add_i32 s12, s6, s12
	s_and_b32 s13, s12, 0xf8
	s_ashr_i32 s3, s2, 31
	s_sub_i32 s6, s6, s13
	s_ashr_i32 s7, s7, 5
	s_lshr_b32 s3, s3, 25
	s_lshl_b32 s7, s7, 3
	s_sext_i32_i8 s6, s6
	s_add_i32 s3, s2, s3
	s_add_i32 s13, s7, s6
	s_and_b32 s6, s3, 0xff80
	s_sub_i32 s2, s2, s6
	s_bfe_i32 s6, s2, 0x80000
	s_bfe_u32 s6, s6, 0x3000c
	s_add_i32 s6, s2, s6
	s_and_b32 s7, s6, 0xf8
	s_sub_i32 s2, s2, s7
	s_ashr_i32 s3, s3, 7
	s_lshl_b32 s3, s3, 3
	s_sext_i32_i8 s2, s2
	s_add_i32 s7, s3, s2
	s_movk_i32 s2, 0x3ff
	v_and_or_b32 v0, v0, s2, v200
	s_bfe_i32 s2, s12, 0x80000
	s_sext_i32_i16 s2, s2
	s_bfe_i32 s3, s6, 0x80000
	s_sext_i32_i16 s3, s3
	s_ashr_i32 s6, s2, 3
	s_lshr_b32 s2, s2, 3
	v_writelane_b32 v254, s6, 48
	s_bfe_i64 s[14:15], s[2:3], 0x100000
	v_writelane_b32 v254, s14, 49
	s_ashr_i32 s2, s3, 3
	s_nop 0
	v_writelane_b32 v254, s15, 50
	v_writelane_b32 v254, s2, 51
	s_lshr_b32 s2, s3, 3
	s_bfe_i64 s[2:3], s[2:3], 0x100000
	v_writelane_b32 v254, s2, 52
	s_nop 1
	v_writelane_b32 v254, s3, 53
	v_writelane_b32 v254, s13, 54
	s_ashr_i32 s2, s13, 31
	v_writelane_b32 v254, s2, 55
	v_writelane_b32 v254, s7, 56
	s_ashr_i32 s2, s7, 31
	v_writelane_b32 v254, s2, 57
	s_add_u32 s2, s76, 0xc00
	s_addc_u32 s3, s77, 0
	v_writelane_b32 v254, s2, 58
	s_nop 1
	v_writelane_b32 v254, s3, 59
	s_lshl_b32 s2, s62, 5
	v_writelane_b32 v254, s2, 60
	s_waitcnt lgkmcnt(0)
	s_add_u32 s0, s40, 0xc00
	v_writelane_b32 v254, s40, 61
	s_addc_u32 s1, s41, 0
	s_nop 0
	v_writelane_b32 v255, s43, 0
	v_writelane_b32 v255, s44, 1
	v_writelane_b32 v255, s45, 2
	v_writelane_b32 v255, s46, 3
	v_writelane_b32 v255, s47, 4
	v_writelane_b32 v255, s48, 5
	v_writelane_b32 v255, s49, 6
	v_writelane_b32 v255, s50, 7
	v_writelane_b32 v255, s51, 8
	v_writelane_b32 v255, s52, 9
	v_writelane_b32 v255, s53, 10
	v_writelane_b32 v255, s54, 11
	v_writelane_b32 v255, s55, 12
	v_writelane_b32 v255, s0, 13
	v_writelane_b32 v254, s41, 62
	v_writelane_b32 v254, s42, 63
	v_writelane_b32 v255, s1, 14
	s_add_i32 s0, 16, 0x4800
	v_writelane_b32 v255, s0, 15
	v_cmp_eq_u32_e64 s[0:1], 0, v0
	s_nop 1
	v_writelane_b32 v255, s0, 16
	s_nop 1
	v_writelane_b32 v255, s1, 17
	v_writelane_b32 v255, s38, 18
	s_nop 1
	v_writelane_b32 v255, s39, 19
	v_writelane_b32 v255, s58, 20
	s_nop 1
	v_writelane_b32 v255, s59, 21
	v_writelane_b32 v255, s92, 22
	s_branch .LBB0_11

.LBB0_15:
	v_readlane_b32 s2, v255, 48
	s_cmp_eq_u32 s2, 0
	s_cbranch_scc1 .Lsq_std
	s_mov_b32 s3, 0x48240
	s_bitcmp1_b32 s3, s80
	s_cbranch_scc0 .Lsq_inN
	s_add_i32 s80, s80, 1
	s_mov_b64 s[0:1], -1
	s_branch .LBB0_423
.Lsq_inN:
	s_cmp_eq_u32 s2, 1
	s_cbranch_scc0 .Lsq_std
	s_add_i32 s80, s80, -1
	s_mov_b32 s2, 2
	v_writelane_b32 v255, s2, 48
	s_barrier
	s_mov_b64 s[0:1], 0
	s_branch .LBB0_477
.Lsq_std:
	s_add_i32 s80, s80, 1
	s_cmp_ge_i32 s80, s81
	s_mov_b64 s[0:1], -1
	s_cbranch_scc1 .LBB0_10
	s_mov_b32 s2, 0
	s_bitcmp1_b32 s61, 6
	s_cbranch_scc0 .Lsq_setm
	s_mov_b32 s3, 0x48240
	s_bitcmp1_b32 s3, s80
	s_cselect_b32 s2, 1, 0
.Lsq_setm:
	v_writelane_b32 v255, s2, 48
	s_branch .LBB0_423
.LBB0_16:
	s_cmp_eq_u32 s80, 19
	s_mov_b64 s[0:1], -1
	s_cbranch_scc0 .LBB0_22
	s_waitcnt vmcnt(0)
	v_mov_b32_e32 v0, v200
	s_load_dword s0, s[38:39], 0x0
	v_ashrrev_i32_e32 v2, 6, v0
	v_add_u32_e32 v49, s61, v2
	v_sub_u32_e32 v2, 0, v49
	v_max_i32_e32 v2, v49, v2
	s_waitcnt lgkmcnt(0)
	s_bfe_i32 s19, s0, 0x1d0000
	s_abs_i32 s1, s19
	v_cvt_f32_u32_e32 v1, s1
	v_xor_b32_e32 v3, s19, v49
	s_sub_i32 s6, 0, s1
	v_ashrrev_i32_e32 v50, 31, v3
	v_rcp_iflag_f32_e32 v1, v1
	s_mov_b32 s20, 0x800000
	v_mul_f32_e32 v1, 0x4f7ffffe, v1
	v_cvt_u32_f32_e32 v1, v1
	v_mul_lo_u32 v3, s6, v1
	v_mul_hi_u32 v3, v1, v3
	v_add_u32_e32 v1, v1, v3
	v_mul_hi_u32 v1, v2, v1
	v_mul_lo_u32 v3, v1, s1
	v_sub_u32_e32 v2, v2, v3
	v_add_u32_e32 v4, 1, v1
	v_cmp_le_u32_e32 vcc, s1, v2
	v_subrev_u32_e32 v3, s1, v2
	s_nop 0
	v_cndmask_b32_e32 v1, v1, v4, vcc
	v_cndmask_b32_e32 v2, v2, v3, vcc
	v_add_u32_e32 v3, 1, v1
	v_cmp_le_u32_e32 vcc, s1, v2
	s_nop 1
	v_cndmask_b32_e32 v1, v1, v3, vcc
	v_xor_b32_e32 v51, v1, v50
	v_sub_u32_e32 v16, v51, v50
	s_bfe_u32 s100, s61, 0x30003
	v_mov_b32_e32 v16, s100
	v_cmp_gt_i32_e32 vcc, 8, v16
	s_and_saveexec_b64 s[6:7], vcc
	s_cbranch_execz .LBB0_21
	v_lshlrev_b32_e32 v1, 12, v16
	v_mul_lo_u32 v2, v16, s19
	v_add_u32_e32 v3, v1, v49
	v_sub_u32_e32 v48, v3, v2
	v_add_u32_e32 v72, 0x1000, v1
	s_lshr_b32 s101, s61, 6
	s_and_b32 s100, s101, 7
	s_lshr_b32 s101, s101, 3
	s_lshl_b32 s100, s100, 8
	s_lshl_b32 s101, s101, 3
	s_add_i32 s101, s101, s100
	s_bfe_u32 s100, s61, 0x30003
	s_lshl_b32 s100, s100, 12
	s_add_i32 s101, s101, s100
	v_readlane_b32 s100, v255, 48
	s_cmp_eq_u32 s100, 2
	s_cselect_b32 vcc_lo, 0x800, 0
	s_add_i32 s101, s101, vcc_lo
	s_cmp_lg_u32 s100, 0
	s_cselect_b32 s100, 1, 0
	v_lshrrev_b32_e32 v48, 6, v200
	v_add_u32_e32 v48, s101, v48
	v_and_b32_e32 v72, 0xffffff00, v48
	v_add_u32_e32 v72, 0x100, v72
	v_cmp_lt_i32_e32 vcc, v48, v72
	s_and_b64 exec, exec, vcc
	s_cbranch_execz .LBB0_21
	v_readlane_b32 s12, v253, 4
	v_readlane_b32 s13, v253, 5
	v_and_b32_e32 v52, 63, v0
	v_lshlrev_b32_e32 v128, 4, v52
	v_mov_b64_e32 v[18:19], s[12:13]
	v_mad_i64_i32 v[18:19], s[12:13], v16, s84, v[18:19]
	v_readlane_b32 s12, v253, 2
	v_readlane_b32 s13, v253, 3
	v_lshl_add_u64 v[36:37], v[18:19], 0, v[128:129]
	global_load_dwordx4 v[0:3], v128, s[74:75]
	global_load_dwordx4 v[4:7], v128, s[74:75] offset:1024
	global_load_dwordx4 v[8:11], v128, s[74:75] offset:2048
	global_load_dwordx4 v[12:15], v128, s[74:75] offset:3072
	v_mov_b64_e32 v[18:19], s[12:13]
	v_mad_i64_i32 v[16:17], s[12:13], v16, s84, v[18:19]
	v_lshl_add_u64 v[44:45], v[16:17], 0, v[128:129]
	global_load_dwordx4 v[16:19], v[36:37], off offset:3072
	global_load_dwordx4 v[20:23], v[36:37], off offset:2048
	global_load_dwordx4 v[24:27], v[44:45], off offset:3072
	global_load_dwordx4 v[28:31], v[44:45], off offset:2048
	global_load_dwordx4 v[32:35], v[36:37], off offset:1024
	s_nop 0
	global_load_dwordx4 v[36:39], v[36:37], off
	s_nop 0
	global_load_dwordx4 v[40:43], v[44:45], off offset:1024
	s_nop 0
	global_load_dwordx4 v[44:47], v[44:45], off
	v_cmp_lt_i32_e32 vcc, v206, v205
	v_readlane_b32 s14, v254, 58
	s_mov_b32 s1, 0
	v_cndmask_b32_e32 v53, v204, v206, vcc
	v_cmp_lt_i32_e32 vcc, v207, v205
	v_lshlrev_b32_e32 v73, 2, v53
	s_mov_b32 s0, 32
	v_cndmask_b32_e32 v53, v204, v207, vcc
	v_cmp_lt_i32_e32 vcc, v252, v205
	v_lshlrev_b32_e32 v74, 2, v53
	v_readlane_b32 s15, v254, 59
	v_cndmask_b32_e32 v53, v204, v252, vcc
	v_lshlrev_b32_e32 v75, 2, v53
	v_xor_b32_e32 v53, 8, v204
	v_cmp_lt_i32_e32 vcc, v53, v205
	s_lshl_b64 s[12:13], s[0:1], 11
	s_mov_b64 s[16:17], 0
	v_cndmask_b32_e32 v53, v204, v53, vcc
	v_cmp_lt_i32_e32 vcc, v210, v205
	v_lshlrev_b32_e32 v76, 2, v53
	s_nop 0
	v_cndmask_b32_e32 v53, v204, v210, vcc
	v_cmp_lt_i32_e32 vcc, v211, v205
	v_lshlrev_b32_e32 v77, 2, v53
	s_nop 0
	v_cndmask_b32_e32 v53, v204, v211, vcc
	v_lshlrev_b32_e32 v78, 2, v53
	v_sub_u32_e32 v53, v50, v51
	v_mul_lo_u32 v53, v53, s19
	v_lshlrev_b32_e32 v51, 12, v51
	v_add3_u32 v49, v49, v53, v51
	v_lshlrev_b32_e32 v50, 12, v50
	v_sub_u32_e32 v79, v49, v50
	v_mov_b32_e32 v79, v48
	v_ashrrev_i32_e32 v49, 31, v48
	v_lshlrev_b64 v[50:51], 11, v[48:49]
	v_lshlrev_b64 v[48:49], 12, v[48:49]
	v_lshl_or_b32 v50, v52, 3, v50
	v_or_b32_e32 v48, v48, v128
	v_lshl_add_u64 v[64:65], s[4:5], 0, v[50:51]
	v_lshl_add_u64 v[66:67], s[14:15], 0, v[48:49]
	s_lshl_b64 s[14:15], s[0:1], 12

.LBB0_24:
	s_movk_i32 s2, 0x400
	s_movk_i32 s0, 0xb00
	s_add_i32 s1, s80, -1
	v_writelane_b32 v255, s2, 23
	s_mov_b32 s96, 0xc2fc0000
	s_mov_b32 s19, 0x800000
	v_writelane_b32 v255, s3, 24
	s_mul_hi_i32 s2, s1, 0x38e38e39
	s_lshr_b32 s3, s2, 31
	s_ashr_i32 s2, s2, 1
	s_add_i32 s12, s2, s3
	s_mul_i32 s2, s12, 9
	s_sub_i32 s6, s1, s2
	s_ashr_i32 s13, s12, 31
	s_mul_i32 s2, s12, 0x30000
	s_mul_hi_i32 s1, s12, 0x30000
	s_add_u32 s2, s58, s2
	s_addc_u32 s3, s59, s1
	s_add_i32 s1, s80, 7
	s_cmp_lt_u32 s1, 17
	v_writelane_b32 v255, s2, 25
	s_cselect_b64 s[42:43], -1, 0
	s_cmp_gt_u32 s1, 16
	v_writelane_b32 v255, s3, 26
	s_cselect_b64 s[2:3], -1, 0
	v_writelane_b32 v255, s2, 27
	s_nop 1
	v_writelane_b32 v255, s3, 28
	s_lshl_b32 s2, s12, 10
	s_ashr_i32 s3, s2, 31
	v_writelane_b32 v255, s2, 29
	s_nop 1
	v_writelane_b32 v255, s3, 30
	v_writelane_b32 v255, s12, 31
	s_lshl_b32 s2, s12, 8
	s_cmp_lt_i32 s6, 4
	v_writelane_b32 v255, s13, 32
	v_writelane_b32 v255, s2, 33
	s_nop 1
	v_writelane_b32 v255, s3, 34
	v_writelane_b32 v255, s6, 35
	s_mov_b64 s[2:3], -1
	s_cbranch_scc1 .LBB0_204
	v_readlane_b32 s1, v255, 35
	s_cmp_lt_i32 s1, 6
	s_cbranch_scc1 .LBB0_119
	v_readlane_b32 s1, v255, 35
	s_cmp_lt_i32 s1, 7
	s_cbranch_scc1 .LBB0_112
	v_readlane_b32 s1, v255, 35
	s_cmp_lt_i32 s1, 8
	s_cbranch_scc1 .LBB0_88
	v_readlane_b32 s1, v255, 35
	s_cmp_eq_u32 s1, 8
	s_cbranch_scc0 .LBB0_87
	v_readlane_b32 s2, v253, 14
	s_waitcnt vmcnt(0)
	v_mov_b32_e32 v12, v200
	v_readlane_b32 s3, v253, 15
	s_andn2_b64 vcc, exec, s[2:3]
	v_readfirstlane_b32 s16, v12
	s_cbranch_vccnz .LBB0_87
	v_lshlrev_b32_e32 v0, 4, v12
	v_add_u32_e32 v1, 0x2000, v0
	v_ashrrev_i32_e32 v2, 31, v1
	v_lshrrev_b32_e32 v2, 22, v2
	v_add_u32_e32 v2, v1, v2
	v_ashrrev_i32_e32 v2, 10, v2
	v_mul_i32_i24_e32 v3, 0x400, v2
	v_sub_u32_e32 v1, v1, v3
	v_lshrrev_b32_e32 v3, 4, v1
	v_bitop3_b32 v1, v3, v1, 32 bitop3:0x6c
	v_ashrrev_i32_e32 v3, 31, v1
	v_readlane_b32 s20, v255, 31
	v_lshrrev_b32_e32 v3, 26, v3
	s_ashr_i32 s14, s16, 6
	s_ashr_i32 s1, s0, 31
	v_readlane_b32 s21, v255, 32
	v_add_u32_e32 v3, v1, v3
	v_lshlrev_b32_e32 v5, 3, v2
	s_ashr_i32 s15, s16, 8
	s_lshl_b64 s[2:3], s[0:1], 8
	s_lshl_b64 s[6:7], s[0:1], 9
	s_lshl_b32 s35, s14, 10
	s_mul_hi_i32 s12, s20, 0x580000
	s_mul_i32 s13, s20, 0x580000
	v_readlane_b32 s20, v253, 12
	v_ashrrev_i32_e32 v4, 6, v3
	v_and_b32_e32 v5, -16, v5
	v_lshlrev_b32_e32 v2, 5, v2
	v_readlane_b32 s21, v253, 13
	s_add_u32 s36, s20, s13
	v_add_u32_e32 v5, v4, v5
	v_and_b32_e32 v13, 32, v2
	v_and_b32_e32 v2, 0xc0, v3
	s_addc_u32 s37, s21, s12
	v_and_b32_e32 v4, 3, v4
	s_mov_b32 s12, 0x7fffffe0
	v_lshrrev_b32_e32 v6, 2, v5
	v_lshlrev_b32_e32 v7, 1, v5
	v_sub_u32_e32 v1, v1, v2
	v_and_or_b32 v4, v5, s12, v4
	v_and_b32_e32 v6, 4, v6
	v_and_b32_e32 v7, 24, v7
	v_ashrrev_i16_sdwa v1, v203, sext(v1) dst_sel:DWORD dst_unused:UNUSED_PAD src0_sel:DWORD src1_sel:BYTE_0
	v_or3_b32 v4, v4, v6, v7
	v_bfe_i32 v14, v1, 0, 16
	v_mul_lo_u32 v4, v4, s0
	v_add_u32_e32 v1, v13, v14
	v_mul_lo_u32 v15, v5, s0
	v_add_lshl_u32 v140, v4, v1, 1
	v_add_lshl_u32 v142, v1, v15, 1
	v_bfe_i32 v1, v12, 27, 1
	v_lshrrev_b32_e32 v1, 22, v1
	v_add_u32_e32 v1, v0, v1
	v_and_b32_e32 v1, 0xfffffc00, v1
	v_sub_u32_e32 v0, v0, v1
	v_ashrrev_i32_e32 v2, 31, v12
	v_lshrrev_b32_e32 v1, 4, v0
	v_lshrrev_b32_e32 v2, 26, v2
	v_bitop3_b32 v1, v1, v0, 32 bitop3:0x6c
	v_ashrrev_i32_e32 v0, 31, v0
	v_add_u32_e32 v2, v12, v2
	v_lshrrev_b32_e32 v0, 26, v0
	v_ashrrev_i32_e32 v2, 6, v2
	v_add_u32_e32 v0, v1, v0
	v_lshlrev_b32_e32 v3, 3, v2
	v_ashrrev_i32_e32 v0, 6, v0
	v_and_b32_e32 v3, -16, v3
	v_add_u32_e32 v3, v0, v3
	v_and_b32_e32 v4, 3, v0
	v_and_or_b32 v4, v3, s12, v4
	v_readlane_b32 s12, v254, 55
	v_readlane_b32 s20, v254, 54
	s_mul_i32 s12, s6, s12
	s_mul_hi_u32 s13, s6, s20
	s_add_i32 s17, s13, s12
	s_lshr_b64 s[12:13], s[0:1], 23
	v_readlane_b32 s24, v254, 49
	s_mul_i32 s13, s12, s20
	v_readlane_b32 s25, v254, 50
	v_mul_i32_i24_e32 v0, 64, v0
	s_add_i32 s17, s17, s13
	s_mul_i32 s13, s6, s25
	s_mul_hi_u32 s21, s6, s24
	v_lshrrev_b32_e32 v5, 2, v3
	v_lshlrev_b32_e32 v6, 1, v3
	v_sub_u32_e32 v0, v1, v0
	s_add_i32 s13, s21, s13
	s_mul_i32 s12, s12, s24
	v_and_b32_e32 v5, 4, v5
	v_and_b32_e32 v6, 24, v6
	v_lshlrev_b32_e32 v2, 5, v2
	v_ashrrev_i16_sdwa v0, v203, sext(v0) dst_sel:DWORD dst_unused:UNUSED_PAD src0_sel:DWORD src1_sel:BYTE_0
	s_add_i32 s13, s13, s12
	s_mul_i32 s12, s6, s24
	v_or3_b32 v4, v4, v5, v6
	v_and_b32_e32 v16, 32, v2
	v_bfe_i32 v17, v0, 0, 16
	s_add_u32 s26, s36, s12
	s_load_dword s34, s[38:39], 0x0
	v_mul_lo_u32 v4, v4, s0
	v_add_u32_e32 v0, v16, v17
	s_addc_u32 s27, s37, s13
	s_add_i32 s38, s35, 16
	v_add_lshl_u32 v128, v4, v0, 1
	s_add_i32 m0, s38, 0x10000
	s_mul_i32 s20, s6, s20
	global_load_lds_dwordx4 v128, s[26:27]
	s_add_i32 m0, s38, 0x12000
	s_add_u32 s12, s26, s2
	global_load_lds_dwordx4 v140, s[26:27]
	s_addc_u32 s13, s27, s3
	s_add_i32 m0, s38, 0x14000
	v_mul_lo_u32 v18, v3, s0
	global_load_lds_dwordx4 v128, s[12:13]
	s_add_i32 m0, s38, 0x16000
	s_add_u32 s28, s22, s20
	v_mov_b32_e32 v141, v129
	s_addc_u32 s29, s23, s17
	v_readlane_b32 s100, v255, 48
	s_cmp_eq_u32 s100, 2
	s_cselect_b32 s101, 0xb00000, 0
	s_add_u32 s28, s28, s101
	s_addc_u32 s29, s29, 0
	s_add_i32 s39, s38, 0x2000
	v_add_lshl_u32 v144, v0, v18, 1
	v_lshl_add_u64 v[4:5], s[12:13], 0, v[128:129]
	v_lshl_add_u64 v[6:7], s[12:13], 0, v[140:141]
	global_load_lds_dwordx4 v140, s[12:13]
	s_mov_b32 m0, s38
	s_add_u32 s12, s28, s2
	global_load_lds_dwordx4 v144, s[28:29]
	s_mov_b32 m0, s39
	s_addc_u32 s13, s29, s3
	s_add_i32 s44, s38, 0x4000
	global_load_lds_dwordx4 v142, s[28:29]
	s_mov_b32 m0, s44
	s_add_i32 s45, s38, 0x6000
	global_load_lds_dwordx4 v144, s[12:13]
	s_mov_b32 m0, s45
	v_mov_b32_e32 v145, v129
	global_load_lds_dwordx4 v142, s[12:13]
	v_mov_b32_e32 v143, v129
	s_cmp_eq_u32 s15, 1
	v_lshl_add_u64 v[0:1], s[26:27], 0, v[128:129]
	v_lshl_add_u64 v[2:3], s[26:27], 0, v[140:141]
	v_lshl_add_u64 v[8:9], s[28:29], 0, v[144:145]
	v_lshl_add_u64 v[10:11], s[28:29], 0, v[142:143]
	s_cselect_b64 s[12:13], -1, 0
	s_cmp_lg_u32 s15, 1
	s_cbranch_scc1 .LBB0_32
	s_barrier
.LBB0_32:
	s_add_i32 m0, s38, 0x18000
	v_lshl_add_u64 v[0:1], v[0:1], 0, s[98:99]
	s_waitcnt vmcnt(2)
	s_barrier
	global_load_lds_dwordx4 v[0:1], off
	v_lshl_add_u64 v[0:1], v[2:3], 0, s[98:99]
	s_add_i32 m0, s38, 0x1a000
	s_add_i32 s46, s38, 0x8000
	global_load_lds_dwordx4 v[0:1], off
	v_lshl_add_u64 v[0:1], v[8:9], 0, s[98:99]
	s_mov_b32 m0, s46
	s_add_i32 s47, s38, 0xa000
	global_load_lds_dwordx4 v[0:1], off
	v_lshl_add_u64 v[0:1], v[10:11], 0, s[98:99]
	s_mov_b32 m0, s47
	s_lshr_b32 s1, s1, 26
	global_load_lds_dwordx4 v[0:1], off
	s_add_i32 m0, s38, 0x1c000
	v_lshl_add_u64 v[0:1], v[4:5], 0, s[98:99]
	global_load_lds_dwordx4 v[0:1], off
	v_lshl_add_u64 v[0:1], v[6:7], 0, s[98:99]
	s_add_i32 m0, s38, 0x1e000
	s_add_i32 s1, s0, s1
	global_load_lds_dwordx4 v[0:1], off
	v_lshrrev_b32_e32 v1, 1, v12
	v_and_b32_e32 v1, 24, v1
	v_and_b32_e32 v0, 15, v12
	v_lshlrev_b32_e32 v2, 1, v1
	v_lshl_or_b32 v135, s15, 6, v0
	v_lshl_or_b32 v0, v0, 6, v2
	v_lshlrev_b32_e32 v2, 2, v12
	s_ashr_i32 s48, s1, 6
	s_lshl_b32 s1, s15, 13
	v_and_b32_e32 v2, 32, v2
	v_bitop3_b32 v3, v0, s1, v2 bitop3:0xde
	s_lshl_b32 s1, s14, 5
	s_and_b32 s1, s1, 0x60
	s_lshl_b32 s14, s1, 7
	v_bitop3_b32 v137, v0, s14, v2 bitop3:0xde
	v_add_u32_e32 v0, v18, v16
	s_cmp_gt_i32 s0, 63
	v_or_b32_e32 v156, s1, v1
	v_add_lshl_u32 v0, v0, v17, 1
	v_mov_b32_e32 v1, v129
	s_waitcnt vmcnt(6)
	s_cselect_b64 s[14:15], -1, 0
	s_add_i32 s49, s48, -2
	v_lshl_add_u64 v[146:147], s[2:3], 0, v[0:1]
	v_add_u32_e32 v0, v15, v13
	s_cmpk_lt_u32 s16, 0x100
	v_add_lshl_u32 v0, v0, v14, 1
	s_cselect_b64 s[16:17], -1, 0
	s_waitcnt lgkmcnt(0)
	s_ashr_i32 s50, s34, 31
	v_lshl_add_u64 v[148:149], s[2:3], 0, v[0:1]
	v_readlane_b32 s100, v255, 48
	s_cmp_lg_u32 s100, 0
	s_cselect_b32 s51, 1, 0
	v_add_u32_e32 v157, 16, v3
	v_readlane_b32 s54, v254, 48
	v_readlane_b32 s55, v254, 54
	s_cmp_eq_u32 s100, 2
	s_cselect_b32 s101, 8, 0
	s_add_i32 s55, s55, s101
	s_barrier
	s_branch .LBB0_35

.LBB0_112:
	s_andn2_b64 vcc, exec, s[2:3]
	s_cbranch_vccnz .LBB0_118
	s_waitcnt vmcnt(0)
	v_mov_b32_e32 v0, v200
	s_load_dword s2, s[38:39], 0x0
	v_ashrrev_i32_e32 v1, 6, v0
	v_add_u32_e32 v64, s61, v1
	s_waitcnt lgkmcnt(0)
	s_bfe_i32 s14, s2, 0x1d0000
	s_abs_i32 s0, s14
	v_cvt_f32_u32_e32 v2, s0
	s_sub_i32 s1, 0, s0
	v_xor_b32_e32 v1, s14, v64
	v_ashrrev_i32_e32 v65, 31, v1
	v_rcp_iflag_f32_e32 v2, v2
	v_sub_u32_e32 v1, 0, v64
	v_max_i32_e32 v1, v64, v1
	v_mul_f32_e32 v2, 0x4f7ffffe, v2
	v_cvt_u32_f32_e32 v2, v2
	v_mul_lo_u32 v3, s1, v2
	v_mul_hi_u32 v3, v2, v3
	v_add_u32_e32 v2, v2, v3
	v_mul_hi_u32 v2, v1, v2
	v_mul_lo_u32 v3, v2, s0
	v_sub_u32_e32 v1, v1, v3
	v_cmp_le_u32_e32 vcc, s0, v1
	v_add_u32_e32 v3, 1, v2
	s_nop 0
	v_cndmask_b32_e32 v2, v2, v3, vcc
	v_subrev_u32_e32 v3, s0, v1
	v_cndmask_b32_e32 v1, v1, v3, vcc
	v_cmp_le_u32_e32 vcc, s0, v1
	v_add_u32_e32 v1, 1, v2
	s_nop 0
	v_cndmask_b32_e32 v1, v2, v1, vcc
	v_xor_b32_e32 v67, v1, v65
	v_sub_u32_e32 v16, v67, v65
	s_bfe_u32 s100, s61, 0x30003
	v_mov_b32_e32 v16, s100
	v_cmp_gt_i32_e32 vcc, 8, v16
	s_and_saveexec_b64 s[0:1], vcc
	s_mov_b32 s16, 0x800000
	s_cbranch_execz .LBB0_117
	v_lshlrev_b32_e32 v1, 12, v16
	v_mul_lo_u32 v2, v16, s14
	v_add_u32_e32 v3, v1, v64
	v_sub_u32_e32 v66, v3, v2
	v_add_u32_e32 v77, 0x1000, v1
	s_lshr_b32 s101, s61, 6
	s_and_b32 s100, s101, 7
	s_lshr_b32 s101, s101, 3
	s_lshl_b32 s100, s100, 8
	s_lshl_b32 s101, s101, 3
	s_add_i32 s101, s101, s100
	s_bfe_u32 s100, s61, 0x30003
	s_lshl_b32 s100, s100, 12
	s_add_i32 s101, s101, s100
	v_readlane_b32 s100, v255, 48
	s_cmp_eq_u32 s100, 2
	s_cselect_b32 vcc_lo, 0x800, 0
	s_add_i32 s101, s101, vcc_lo
	s_cmp_lg_u32 s100, 0
	s_cselect_b32 s100, 1, 0
	v_lshrrev_b32_e32 v66, 6, v200
	v_add_u32_e32 v66, s101, v66
	v_and_b32_e32 v77, 0xffffff00, v66
	v_add_u32_e32 v77, 0x100, v77
	v_cmp_lt_i32_e32 vcc, v66, v77
	s_and_b64 exec, exec, vcc
	s_cbranch_execz .LBB0_117
	v_readlane_b32 s6, v255, 29
	v_readlane_b32 s7, v255, 30
	s_lshl_b64 s[6:7], s[6:7], 2
	s_add_u32 s6, s68, s6
	v_and_b32_e32 v68, 63, v0
	s_addc_u32 s7, s69, s7
	v_lshlrev_b32_e32 v128, 4, v68
	global_load_dwordx4 v[0:3], v128, s[6:7]
	global_load_dwordx4 v[4:7], v128, s[6:7] offset:1024
	global_load_dwordx4 v[8:11], v128, s[6:7] offset:2048
	global_load_dwordx4 v[12:15], v128, s[6:7] offset:3072
	v_readlane_b32 s6, v255, 25
	v_readlane_b32 s7, v255, 26
	s_movk_i32 s3, 0x4000
	s_mov_b64 s[12:13], 0x2000
	v_mov_b64_e32 v[18:19], s[6:7]
	v_mad_i64_i32 v[16:17], s[6:7], v16, s84, v[18:19]
	v_lshl_add_u64 v[44:45], v[16:17], 0, v[128:129]
	v_add_co_u32_e32 v16, vcc, s3, v44
	s_movk_i32 s3, 0x3000
	s_nop 0
	v_addc_co_u32_e32 v17, vcc, 0, v45, vcc
	global_load_dwordx4 v[16:19], v[16:17], off
	s_mov_b64 s[6:7], 0x4000
	v_lshl_add_u64 v[28:29], v[44:45], 0, s[6:7]
	s_mov_b64 s[6:7], 0x3000
	v_lshl_add_u64 v[32:33], v[44:45], 0, s[6:7]
	v_lshl_add_u64 v[40:41], v[44:45], 0, s[12:13]
	s_and_b64 s[6:7], s[42:43], exec
	v_readlane_b32 s40, v254, 61
	v_readlane_b32 s41, v254, 62
	s_cselect_b32 s7, s41, s77
	s_cselect_b32 s6, s40, s76
	s_mov_b32 s13, 0
	s_mov_b32 s12, 32
	v_readlane_b32 s42, v254, 63
	v_readlane_b32 s43, v255, 0
	v_readlane_b32 s44, v255, 1
	v_readlane_b32 s45, v255, 2
	v_readlane_b32 s46, v255, 3
	v_readlane_b32 s47, v255, 4
	v_readlane_b32 s48, v255, 5
	v_readlane_b32 s49, v255, 6
	v_readlane_b32 s50, v255, 7
	v_readlane_b32 s51, v255, 8
	v_readlane_b32 s52, v255, 9
	v_readlane_b32 s53, v255, 10
	v_readlane_b32 s54, v255, 11
	v_readlane_b32 s55, v255, 12
	s_waitcnt vmcnt(0)
	v_pk_add_f32 v[50:51], v[16:17], 1.0 op_sel_hi:[1,0]
	v_add_co_u32_e32 v16, vcc, s3, v44
	v_pk_add_f32 v[48:49], v[18:19], 1.0 op_sel_hi:[1,0]
	s_nop 0
	v_addc_co_u32_e32 v17, vcc, 0, v45, vcc
	global_load_dwordx4 v[16:19], v[16:17], off
	s_nop 0
	global_load_dwordx4 v[20:23], v[28:29], off offset:1024
	s_movk_i32 s3, 0x2000
	v_add_co_u32_e32 v44, vcc, s3, v44
	s_lshl_b64 s[2:3], s[12:13], 11
	s_nop 0
	v_addc_co_u32_e32 v45, vcc, 0, v45, vcc
	v_cmp_lt_i32_e32 vcc, v206, v205
	s_waitcnt vmcnt(0)
	v_pk_add_f32 v[52:53], v[22:23], 1.0 op_sel_hi:[1,0]
	v_pk_add_f32 v[54:55], v[20:21], 1.0 op_sel_hi:[1,0]
	global_load_dwordx4 v[20:23], v[32:33], off offset:1024
	global_load_dwordx4 v[24:27], v[28:29], off offset:2048
	v_cndmask_b32_e32 v69, v204, v206, vcc
	v_cmp_lt_i32_e32 vcc, v207, v205
	v_lshlrev_b32_e32 v80, 2, v69
	s_waitcnt vmcnt(0)
	v_pk_add_f32 v[56:57], v[26:27], 1.0 op_sel_hi:[1,0]
	v_pk_add_f32 v[58:59], v[24:25], 1.0 op_sel_hi:[1,0]
	global_load_dwordx4 v[24:27], v[32:33], off offset:2048
	s_nop 0
	global_load_dwordx4 v[28:31], v[28:29], off offset:3072
	v_cndmask_b32_e32 v69, v204, v207, vcc
	v_cmp_lt_i32_e32 vcc, v252, v205
	v_lshlrev_b32_e32 v81, 2, v69
	s_waitcnt vmcnt(0)
	v_pk_add_f32 v[60:61], v[30:31], 1.0 op_sel_hi:[1,0]
	v_pk_add_f32 v[62:63], v[28:29], 1.0 op_sel_hi:[1,0]
	global_load_dwordx4 v[28:31], v[32:33], off offset:3072
	s_nop 0
	global_load_dwordx4 v[32:35], v[40:41], off offset:3072
	global_load_dwordx4 v[36:39], v[40:41], off offset:2048
	s_nop 0
	global_load_dwordx4 v[40:43], v[40:41], off offset:1024
	v_cndmask_b32_e32 v69, v204, v252, vcc
	global_load_dwordx4 v[44:47], v[44:45], off
	v_lshlrev_b32_e32 v82, 2, v69
	v_xor_b32_e32 v69, 8, v204
	v_cmp_lt_i32_e32 vcc, v69, v205
	s_nop 1
	v_cndmask_b32_e32 v69, v204, v69, vcc
	v_cmp_lt_i32_e32 vcc, v210, v205
	v_lshlrev_b32_e32 v83, 2, v69
	s_nop 0
	v_cndmask_b32_e32 v69, v204, v210, vcc
	v_cmp_lt_i32_e32 vcc, v211, v205
	v_lshlrev_b32_e32 v84, 2, v69
	s_nop 0
	v_cndmask_b32_e32 v69, v204, v211, vcc
	v_lshlrev_b32_e32 v85, 2, v69
	v_sub_u32_e32 v69, v65, v67
	v_mul_lo_u32 v69, v69, s14
	v_lshlrev_b32_e32 v67, 12, v67
	v_add3_u32 v64, v64, v69, v67
	v_lshlrev_b32_e32 v65, 12, v65
	v_ashrrev_i32_e32 v67, 31, v66
	v_sub_u32_e32 v86, v64, v65
	v_mov_b32_e32 v86, v66
	v_lshlrev_b64 v[64:65], 11, v[66:67]
	v_lshlrev_b64 v[66:67], 12, v[66:67]
	v_or_b32_e32 v66, v66, v128
	v_lshl_or_b32 v64, v68, 3, v64
	v_lshl_add_u64 v[66:67], s[6:7], 0, v[66:67]
	s_mov_b64 s[6:7], 0xc00
	v_lshl_add_u64 v[64:65], s[4:5], 0, v[64:65]
	v_lshl_add_u64 v[66:67], v[66:67], 0, s[6:7]
	s_lshl_b64 s[6:7], s[12:13], 12
	s_mov_b64 s[12:13], 0

.LBB0_119:
	s_andn2_b64 vcc, exec, s[2:3]
	s_cbranch_vccnz .LBB0_203
	v_readlane_b32 s0, v255, 35
	s_cmp_gt_i32 s0, 4
	s_mov_b64 s[0:1], -1
	s_cbranch_scc0 .LBB0_180
	v_readlane_b32 s0, v253, 14
	s_waitcnt vmcnt(0)
	v_mov_b32_e32 v12, v200
	v_readlane_b32 s1, v253, 15
	s_andn2_b64 vcc, exec, s[0:1]
	v_readfirstlane_b32 s0, v12
	s_cbranch_vccnz .LBB0_179
	v_lshlrev_b32_e32 v0, 4, v12
	v_add_u32_e32 v1, 0x2000, v0
	v_ashrrev_i32_e32 v2, 31, v1
	v_lshrrev_b32_e32 v2, 22, v2
	v_add_u32_e32 v2, v1, v2
	v_ashrrev_i32_e32 v2, 10, v2
	v_mul_i32_i24_e32 v3, 0x400, v2
	v_sub_u32_e32 v1, v1, v3
	v_lshrrev_b32_e32 v3, 4, v1
	v_bitop3_b32 v1, v3, v1, 32 bitop3:0x6c
	v_ashrrev_i32_e32 v3, 31, v1
	v_lshrrev_b32_e32 v3, 26, v3
	v_readlane_b32 s2, v255, 23
	v_readlane_b32 s12, v255, 31
	v_add_u32_e32 v3, v1, v3
	v_lshlrev_b32_e32 v5, 3, v2
	s_ashr_i32 s1, s0, 6
	v_readlane_b32 s3, v255, 24
	s_mov_b32 s20, s2
	s_ashr_i32 s21, s2, 31
	v_readlane_b32 s13, v255, 32
	v_ashrrev_i32_e32 v4, 6, v3
	v_and_b32_e32 v5, -16, v5
	v_lshlrev_b32_e32 v2, 5, v2
	s_ashr_i32 s14, s0, 8
	s_lshl_b64 s[2:3], s[20:21], 8
	s_lshl_b64 s[6:7], s[20:21], 9
	s_lshl_b32 s35, s1, 10
	s_lshl_b64 s[12:13], s[12:13], 21
	v_readlane_b32 s16, v253, 25
	v_add_u32_e32 v5, v4, v5
	v_and_b32_e32 v13, 32, v2
	v_and_b32_e32 v2, 0xc0, v3
	s_add_u32 s36, s16, s12
	v_and_b32_e32 v4, 3, v4
	s_mov_b32 s12, 0x7fffffe0
	v_lshrrev_b32_e32 v6, 2, v5
	v_lshlrev_b32_e32 v7, 1, v5
	v_sub_u32_e32 v1, v1, v2
	v_and_or_b32 v4, v5, s12, v4
	v_and_b32_e32 v6, 4, v6
	v_and_b32_e32 v7, 24, v7
	v_ashrrev_i16_sdwa v1, v203, sext(v1) dst_sel:DWORD dst_unused:UNUSED_PAD src0_sel:DWORD src1_sel:BYTE_0
	v_or3_b32 v4, v4, v6, v7
	v_bfe_i32 v14, v1, 0, 16
	v_mul_lo_u32 v4, v4, s20
	v_add_u32_e32 v1, v13, v14
	v_mul_lo_u32 v15, v5, s20
	v_add_lshl_u32 v140, v4, v1, 1
	v_add_lshl_u32 v142, v1, v15, 1
	v_bfe_i32 v1, v12, 27, 1
	v_lshrrev_b32_e32 v1, 22, v1
	v_add_u32_e32 v1, v0, v1
	v_and_b32_e32 v1, 0xfffffc00, v1
	v_sub_u32_e32 v0, v0, v1
	v_ashrrev_i32_e32 v2, 31, v12
	v_lshrrev_b32_e32 v1, 4, v0
	v_lshrrev_b32_e32 v2, 26, v2
	v_bitop3_b32 v1, v1, v0, 32 bitop3:0x6c
	v_ashrrev_i32_e32 v0, 31, v0
	v_add_u32_e32 v2, v12, v2
	v_lshrrev_b32_e32 v0, 26, v0
	v_ashrrev_i32_e32 v2, 6, v2
	v_add_u32_e32 v0, v1, v0
	v_lshlrev_b32_e32 v3, 3, v2
	v_ashrrev_i32_e32 v0, 6, v0
	v_and_b32_e32 v3, -16, v3
	v_add_u32_e32 v3, v0, v3
	v_and_b32_e32 v4, 3, v0
	v_lshrrev_b32_e32 v5, 2, v3
	v_lshlrev_b32_e32 v6, 1, v3
	v_and_or_b32 v4, v3, s12, v4
	v_and_b32_e32 v5, 4, v5
	v_and_b32_e32 v6, 24, v6
	v_readlane_b32 s17, v253, 26
	v_or3_b32 v4, v4, v5, v6
	v_readlane_b32 s12, v254, 55
	v_readlane_b32 s16, v254, 54
	s_addc_u32 s37, s17, s13
	v_mul_lo_u32 v4, v4, s20
	v_mul_lo_u32 v18, v3, s20
	s_mul_i32 s12, s6, s12
	s_mul_hi_u32 s13, s6, s16
	v_writelane_b32 v255, s20, 23
	s_add_i32 s15, s13, s12
	s_lshr_b64 s[12:13], s[20:21], 23
	v_writelane_b32 v255, s21, 24
	v_readlane_b32 s20, v254, 49
	s_mul_i32 s13, s12, s16
	v_readlane_b32 s21, v254, 50
	v_mul_i32_i24_e32 v0, 64, v0
	s_add_i32 s15, s15, s13
	s_mul_i32 s13, s6, s21
	s_mul_hi_u32 s17, s6, s20
	v_sub_u32_e32 v0, v1, v0
	s_add_i32 s13, s17, s13
	s_mul_i32 s12, s12, s20
	v_lshlrev_b32_e32 v2, 5, v2
	v_ashrrev_i16_sdwa v0, v203, sext(v0) dst_sel:DWORD dst_unused:UNUSED_PAD src0_sel:DWORD src1_sel:BYTE_0
	s_add_i32 s13, s13, s12
	s_mul_i32 s12, s6, s20
	v_and_b32_e32 v16, 32, v2
	v_bfe_i32 v17, v0, 0, 16
	s_add_u32 s26, s36, s12
	s_load_dword s34, s[38:39], 0x0
	v_add_u32_e32 v0, v16, v17
	s_addc_u32 s27, s37, s13
	s_add_i32 s38, s35, 16
	v_add_lshl_u32 v128, v4, v0, 1
	s_add_i32 m0, s38, 0x10000
	s_mul_i32 s16, s6, s16
	global_load_lds_dwordx4 v128, s[26:27]
	s_add_i32 m0, s38, 0x12000
	s_add_u32 s12, s26, s2
	global_load_lds_dwordx4 v140, s[26:27]
	s_addc_u32 s13, s27, s3
	s_add_i32 m0, s38, 0x14000
	v_mov_b32_e32 v141, v129
	global_load_lds_dwordx4 v128, s[12:13]
	s_add_i32 m0, s38, 0x16000
	s_add_u32 s28, s8, s16
	s_addc_u32 s29, s9, s15
	v_readlane_b32 s100, v255, 48
	s_cmp_eq_u32 s100, 2
	s_cselect_b32 s101, 0x400000, 0
	s_add_u32 s28, s28, s101
	s_addc_u32 s29, s29, 0
	s_add_i32 s39, s38, 0x2000
	v_add_lshl_u32 v144, v0, v18, 1
	v_lshl_add_u64 v[4:5], s[12:13], 0, v[128:129]
	v_lshl_add_u64 v[6:7], s[12:13], 0, v[140:141]
	global_load_lds_dwordx4 v140, s[12:13]
	s_mov_b32 m0, s38
	s_add_u32 s12, s28, s2
	global_load_lds_dwordx4 v144, s[28:29]
	s_mov_b32 m0, s39
	s_addc_u32 s13, s29, s3
	s_add_i32 s42, s38, 0x4000
	global_load_lds_dwordx4 v142, s[28:29]
	s_mov_b32 m0, s42
	s_add_i32 s43, s38, 0x6000
	global_load_lds_dwordx4 v144, s[12:13]
	s_mov_b32 m0, s43
	v_mov_b32_e32 v145, v129
	global_load_lds_dwordx4 v142, s[12:13]
	v_mov_b32_e32 v143, v129
	s_cmp_eq_u32 s14, 1
	v_lshl_add_u64 v[0:1], s[26:27], 0, v[128:129]
	v_lshl_add_u64 v[2:3], s[26:27], 0, v[140:141]
	v_lshl_add_u64 v[8:9], s[28:29], 0, v[144:145]
	v_lshl_add_u64 v[10:11], s[28:29], 0, v[142:143]
	s_cselect_b64 s[12:13], -1, 0
	s_cmp_lg_u32 s14, 1
	s_cbranch_scc1 .LBB0_124
	s_barrier
.LBB0_124:
	s_add_i32 m0, s38, 0x18000
	v_lshl_add_u64 v[0:1], v[0:1], 0, s[98:99]
	s_waitcnt vmcnt(2)
	s_barrier
	global_load_lds_dwordx4 v[0:1], off
	v_lshl_add_u64 v[0:1], v[2:3], 0, s[98:99]
	s_add_i32 m0, s38, 0x1a000
	s_add_i32 s44, s38, 0x8000
	global_load_lds_dwordx4 v[0:1], off
	v_lshl_add_u64 v[0:1], v[8:9], 0, s[98:99]
	s_mov_b32 m0, s44
	s_add_i32 s45, s38, 0xa000
	global_load_lds_dwordx4 v[0:1], off
	v_lshl_add_u64 v[0:1], v[10:11], 0, s[98:99]
	s_mov_b32 m0, s45
	v_readlane_b32 s16, v255, 23
	global_load_lds_dwordx4 v[0:1], off
	s_add_i32 m0, s38, 0x1c000
	v_lshl_add_u64 v[0:1], v[4:5], 0, s[98:99]
	global_load_lds_dwordx4 v[0:1], off
	v_lshl_add_u64 v[0:1], v[6:7], 0, s[98:99]
	s_add_i32 m0, s38, 0x1e000
	v_readlane_b32 s17, v255, 24
	global_load_lds_dwordx4 v[0:1], off
	v_lshrrev_b32_e32 v1, 1, v12
	v_and_b32_e32 v1, 24, v1
	v_and_b32_e32 v0, 15, v12
	v_lshlrev_b32_e32 v2, 1, v1
	v_lshl_or_b32 v135, s14, 6, v0
	v_lshl_or_b32 v0, v0, 6, v2
	v_lshlrev_b32_e32 v2, 2, v12
	s_lshl_b32 s1, s1, 5
	s_lshr_b32 s15, s17, 26
	s_lshl_b32 s14, s14, 13
	v_and_b32_e32 v2, 32, v2
	s_and_b32 s1, s1, 0x60
	s_add_i32 s15, s16, s15
	v_bitop3_b32 v3, v0, s14, v2 bitop3:0xde
	s_lshl_b32 s14, s1, 7
	s_ashr_i32 s46, s15, 6
	v_bitop3_b32 v137, v0, s14, v2 bitop3:0xde
	v_add_u32_e32 v0, v18, v16
	s_cmp_gt_i32 s16, 63
	v_or_b32_e32 v156, s1, v1
	v_add_lshl_u32 v0, v0, v17, 1
	v_mov_b32_e32 v1, v129
	s_waitcnt vmcnt(6)
	s_cselect_b64 s[14:15], -1, 0
	s_add_i32 s47, s46, -2
	v_lshl_add_u64 v[146:147], s[2:3], 0, v[0:1]
	v_add_u32_e32 v0, v15, v13
	s_cmpk_lt_u32 s0, 0x100
	v_add_lshl_u32 v0, v0, v14, 1
	s_cselect_b64 s[16:17], -1, 0
	s_waitcnt lgkmcnt(0)
	s_ashr_i32 s48, s34, 31
	v_lshl_add_u64 v[148:149], s[2:3], 0, v[0:1]
	v_readlane_b32 s100, v255, 48
	s_cmp_lg_u32 s100, 0
	s_cselect_b32 s49, 1, 0
	v_add_u32_e32 v157, 16, v3
	v_readlane_b32 s52, v254, 48
	v_readlane_b32 s53, v254, 54
	s_cmp_eq_u32 s100, 2
	s_cselect_b32 s101, 8, 0
	s_add_i32 s53, s53, s101
	s_barrier
	s_branch .LBB0_127

.LBB0_380:
	s_andn2_b64 vcc, exec, s[0:1]
	s_cbranch_vccnz .LBB0_411
	v_readlane_b32 s0, v255, 35
	s_cmp_eq_u32 s0, 0
	s_cbranch_scc0 .LBB0_411
	v_readlane_b32 s0, v255, 25
	v_readlane_b32 s6, v255, 27
	v_readlane_b32 s1, v255, 26
	s_add_u32 s0, s0, 0x1000
	v_readlane_b32 s7, v255, 28
	s_addc_u32 s1, s1, 0
	s_mov_b64 s[2:3], -1
	s_and_b64 vcc, exec, s[6:7]
	s_cbranch_vccz .LBB0_388
	s_waitcnt vmcnt(0)
	v_mov_b32_e32 v0, v200
	s_load_dword s12, s[38:39], 0x0
	v_ashrrev_i32_e32 v2, 6, v0
	v_add_u32_e32 v66, s61, v2
	v_sub_u32_e32 v2, 0, v66
	v_max_i32_e32 v2, v66, v2
	s_waitcnt lgkmcnt(0)
	s_bfe_i32 s19, s12, 0x1d0000
	s_abs_i32 s2, s19
	v_cvt_f32_u32_e32 v1, s2
	v_xor_b32_e32 v3, s19, v66
	s_sub_i32 s3, 0, s2
	v_ashrrev_i32_e32 v65, 31, v3
	v_rcp_iflag_f32_e32 v1, v1
	s_nop 0
	v_mul_f32_e32 v1, 0x4f7ffffe, v1
	v_cvt_u32_f32_e32 v1, v1
	v_mul_lo_u32 v3, s3, v1
	v_mul_hi_u32 v3, v1, v3
	v_add_u32_e32 v1, v1, v3
	v_mul_hi_u32 v1, v2, v1
	v_mul_lo_u32 v3, v1, s2
	v_sub_u32_e32 v2, v2, v3
	v_add_u32_e32 v4, 1, v1
	v_cmp_le_u32_e32 vcc, s2, v2
	v_subrev_u32_e32 v3, s2, v2
	s_nop 0
	v_cndmask_b32_e32 v1, v1, v4, vcc
	v_cndmask_b32_e32 v2, v2, v3, vcc
	v_add_u32_e32 v3, 1, v1
	v_cmp_le_u32_e32 vcc, s2, v2
	s_nop 1
	v_cndmask_b32_e32 v1, v1, v3, vcc
	v_xor_b32_e32 v67, v1, v65
	v_sub_u32_e32 v16, v67, v65
	s_bfe_u32 s100, s61, 0x30003
	v_mov_b32_e32 v16, s100
	v_cmp_gt_i32_e32 vcc, 8, v16
	s_and_saveexec_b64 s[2:3], vcc
	s_mov_b32 s20, 0x800000
	s_cbranch_execz .LBB0_387
	v_lshlrev_b32_e32 v1, 12, v16
	v_mul_lo_u32 v2, v16, s19
	v_add_u32_e32 v3, v1, v66
	v_sub_u32_e32 v64, v3, v2
	v_add_u32_e32 v104, 0x1000, v1
	s_lshr_b32 s101, s61, 6
	s_and_b32 s100, s101, 7
	s_lshr_b32 s101, s101, 3
	s_lshl_b32 s100, s100, 8
	s_lshl_b32 s101, s101, 3
	s_add_i32 s101, s101, s100
	s_bfe_u32 s100, s61, 0x30003
	s_lshl_b32 s100, s100, 12
	s_add_i32 s101, s101, s100
	v_readlane_b32 s100, v255, 48
	s_cmp_eq_u32 s100, 2
	s_cselect_b32 vcc_lo, 0x800, 0
	s_add_i32 s101, s101, vcc_lo
	s_cmp_lg_u32 s100, 0
	s_cselect_b32 s100, 1, 0
	v_lshrrev_b32_e32 v64, 6, v200
	v_add_u32_e32 v64, s101, v64
	v_and_b32_e32 v104, 0xffffff00, v64
	v_add_u32_e32 v104, 0x100, v104
	v_cmp_lt_i32_e32 vcc, v64, v104
	s_and_b64 exec, exec, vcc
	s_cbranch_execz .LBB0_387
	v_readlane_b32 s6, v255, 29
	v_readlane_b32 s7, v255, 30
	v_readlane_b32 s40, v254, 61
	s_lshl_b64 s[6:7], s[6:7], 2
	v_readlane_b32 s48, v255, 5
	v_readlane_b32 s49, v255, 6
	s_add_u32 s6, s48, s6
	v_and_b32_e32 v100, 63, v0
	s_addc_u32 s7, s49, s7
	v_lshlrev_b32_e32 v128, 4, v100
	v_mov_b64_e32 v[18:19], s[0:1]
	global_load_dwordx4 v[0:3], v128, s[6:7]
	global_load_dwordx4 v[4:7], v128, s[6:7] offset:1024
	global_load_dwordx4 v[8:11], v128, s[6:7] offset:2048
	global_load_dwordx4 v[12:15], v128, s[6:7] offset:3072
	v_mad_i64_i32 v[18:19], s[6:7], v16, s84, v[18:19]
	v_readlane_b32 s6, v255, 25
	v_readlane_b32 s7, v255, 26
	v_lshl_add_u64 v[24:25], v[18:19], 0, v[128:129]
	v_xor_b32_e32 v83, 8, v204
	v_mov_b64_e32 v[18:19], s[6:7]
	v_mad_i64_i32 v[16:17], s[6:7], v16, s84, v[18:19]
	s_mov_b32 s6, 0xfffd5000
	v_lshl_add_u64 v[56:57], v[16:17], 0, v[128:129]
	s_mov_b32 s7, -1
	v_lshl_add_u64 v[48:49], v[56:57], 0, s[6:7]
	s_mov_b32 s6, 0xfffd2000
	s_mov_b32 s7, -1
	v_lshl_add_u64 v[52:53], v[56:57], 0, s[6:7]
	s_mov_b32 s6, 0xfffd5000
	global_load_dwordx4 v[68:71], v[24:25], off
	global_load_dwordx4 v[72:75], v[24:25], off offset:1024
	global_load_dwordx4 v[16:19], v[56:57], off
	global_load_dwordx4 v[20:23], v[56:57], off offset:1024
	global_load_dwordx4 v[76:79], v[24:25], off offset:2048
	global_load_dwordx4 v[96:99], v[24:25], off offset:3072
	s_nop 0
	global_load_dwordx4 v[24:27], v[56:57], off offset:2048
	global_load_dwordx4 v[28:31], v[56:57], off offset:3072
	global_load_dwordx4 v[32:35], v[52:53], off offset:3072
	global_load_dwordx4 v[36:39], v[52:53], off offset:2048
	global_load_dwordx4 v[40:43], v[48:49], off offset:2048
	global_load_dwordx4 v[44:47], v[48:49], off offset:1024
	s_nop 0
	global_load_dwordx4 v[48:51], v[48:49], off offset:3072
	s_nop 0
	global_load_dwordx4 v[52:55], v[52:53], off offset:1024
	v_add_co_u32_e32 v58, vcc, s6, v56
	s_mov_b32 s6, 0xfffd2000
	s_nop 0
	v_addc_co_u32_e32 v59, vcc, -1, v57, vcc
	v_add_co_u32_e32 v60, vcc, s6, v56
	v_sub_u32_e32 v86, v65, v67
	s_nop 0
	v_addc_co_u32_e32 v61, vcc, -1, v57, vcc
	global_load_dwordx4 v[56:59], v[58:59], off
	s_nop 0
	global_load_dwordx4 v[60:63], v[60:61], off
	v_cmp_lt_i32_e32 vcc, v206, v205
	v_lshlrev_b32_e32 v87, 12, v65
	v_ashrrev_i32_e32 v65, 31, v64
	v_cndmask_b32_e32 v80, v204, v206, vcc
	v_cmp_lt_i32_e32 vcc, v207, v205
	s_add_i32 s6, s80, -10
	v_readlane_b32 s41, v254, 62
	v_cndmask_b32_e32 v81, v204, v207, vcc
	v_cmp_lt_i32_e32 vcc, v252, v205
	v_lshlrev_b32_e32 v67, 12, v67
	v_lshlrev_b32_e32 v105, 2, v80
	v_cndmask_b32_e32 v82, v204, v252, vcc
	v_cmp_lt_i32_e32 vcc, v83, v205
	v_lshlrev_b32_e32 v106, 2, v81
	v_lshlrev_b32_e32 v107, 2, v82
	v_cndmask_b32_e32 v83, v204, v83, vcc
	v_cmp_lt_i32_e32 vcc, v210, v205
	v_mul_lo_u32 v82, v86, s19
	v_lshlrev_b64 v[80:81], 12, v[64:65]
	v_cndmask_b32_e32 v84, v204, v210, vcc
	v_cmp_lt_i32_e32 vcc, v211, v205
	s_cmp_lt_u32 s6, 9
	v_lshlrev_b64 v[64:65], 11, v[64:65]
	v_cndmask_b32_e32 v85, v204, v211, vcc
	v_add3_u32 v66, v66, v82, v67
	s_cselect_b32 s7, s41, s77
	s_cselect_b32 s6, s40, s76
	s_mov_b32 s15, 0
	s_mov_b32 s14, 32
	v_lshl_or_b32 v64, v100, 3, v64
	v_lshlrev_b32_e32 v108, 2, v83
	v_lshlrev_b32_e32 v109, 2, v84
	v_lshlrev_b32_e32 v110, 2, v85
	v_or_b32_e32 v80, v80, v128
	v_sub_u32_e32 v111, v66, v87
	v_lshrrev_b32_e32 v111, 6, v200
	v_add_u32_e32 v111, s101, v111
	s_lshl_b64 s[12:13], s[14:15], 12
	s_lshl_b64 s[14:15], s[14:15], 11
	s_mov_b64 s[16:17], 0
	v_readlane_b32 s42, v254, 63
	v_readlane_b32 s43, v255, 0
	v_readlane_b32 s44, v255, 1
	v_readlane_b32 s45, v255, 2
	v_readlane_b32 s46, v255, 3
	v_readlane_b32 s47, v255, 4
	v_readlane_b32 s50, v255, 7
	v_readlane_b32 s51, v255, 8
	v_readlane_b32 s52, v255, 9
	v_readlane_b32 s53, v255, 10
	v_readlane_b32 s54, v255, 11
	v_readlane_b32 s55, v255, 12
	s_waitcnt vmcnt(15)
	v_pk_add_f32 v[82:83], v[70:71], 1.0 op_sel_hi:[1,0]
	v_pk_add_f32 v[84:85], v[68:69], 1.0 op_sel_hi:[1,0]
	s_waitcnt vmcnt(14)
	v_pk_add_f32 v[86:87], v[74:75], 1.0 op_sel_hi:[1,0]
	v_pk_add_f32 v[88:89], v[72:73], 1.0 op_sel_hi:[1,0]
	s_waitcnt vmcnt(11)
	v_pk_add_f32 v[90:91], v[78:79], 1.0 op_sel_hi:[1,0]
	v_pk_add_f32 v[92:93], v[76:77], 1.0 op_sel_hi:[1,0]
	s_waitcnt vmcnt(10)
	v_pk_add_f32 v[94:95], v[98:99], 1.0 op_sel_hi:[1,0]
	v_pk_add_f32 v[96:97], v[96:97], 1.0 op_sel_hi:[1,0]
	v_lshl_add_u64 v[98:99], s[4:5], 0, v[64:65]

.LBB0_388:
	s_andn2_b64 vcc, exec, s[2:3]
	s_cbranch_vccnz .LBB0_411
	s_waitcnt vmcnt(0)
	v_mov_b32_e32 v0, v200
	s_load_dword s14, s[38:39], 0x0
	v_ashrrev_i32_e32 v2, 6, v0
	v_add_u32_e32 v34, s61, v2
	v_sub_u32_e32 v2, 0, v34
	v_max_i32_e32 v2, v34, v2
	s_waitcnt lgkmcnt(0)
	s_bfe_i32 s15, s14, 0x1d0000
	s_abs_i32 s2, s15
	v_cvt_f32_u32_e32 v1, s2
	v_xor_b32_e32 v3, s15, v34
	s_sub_i32 s3, 0, s2
	v_ashrrev_i32_e32 v33, 31, v3
	v_rcp_iflag_f32_e32 v1, v1
	s_nop 0
	v_mul_f32_e32 v1, 0x4f7ffffe, v1
	v_cvt_u32_f32_e32 v1, v1
	v_mul_lo_u32 v3, s3, v1
	v_mul_hi_u32 v3, v1, v3
	v_add_u32_e32 v1, v1, v3
	v_mul_hi_u32 v1, v2, v1
	v_mul_lo_u32 v3, v1, s2
	v_sub_u32_e32 v2, v2, v3
	v_add_u32_e32 v4, 1, v1
	v_cmp_le_u32_e32 vcc, s2, v2
	v_subrev_u32_e32 v3, s2, v2
	s_nop 0
	v_cndmask_b32_e32 v1, v1, v4, vcc
	v_cndmask_b32_e32 v2, v2, v3, vcc
	v_add_u32_e32 v3, 1, v1
	v_cmp_le_u32_e32 vcc, s2, v2
	s_nop 1
	v_cndmask_b32_e32 v1, v1, v3, vcc
	v_xor_b32_e32 v35, v1, v33
	v_sub_u32_e32 v16, v35, v33
	s_bfe_u32 s100, s61, 0x30003
	v_mov_b32_e32 v16, s100
	v_cmp_gt_i32_e32 vcc, 8, v16
	s_and_saveexec_b64 s[2:3], vcc
	s_mov_b32 s16, 0x800000
	s_cbranch_execz .LBB0_393
	v_lshlrev_b32_e32 v1, 12, v16
	v_mul_lo_u32 v2, v16, s15
	v_add_u32_e32 v3, v1, v34
	v_sub_u32_e32 v32, v3, v2
	v_add_u32_e32 v52, 0x1000, v1
	s_lshr_b32 s101, s61, 6
	s_and_b32 s100, s101, 7
	s_lshr_b32 s101, s101, 3
	s_lshl_b32 s100, s100, 8
	s_lshl_b32 s101, s101, 3
	s_add_i32 s101, s101, s100
	s_bfe_u32 s100, s61, 0x30003
	s_lshl_b32 s100, s100, 12
	s_add_i32 s101, s101, s100
	v_readlane_b32 s100, v255, 48
	s_cmp_eq_u32 s100, 2
	s_cselect_b32 vcc_lo, 0x800, 0
	s_add_i32 s101, s101, vcc_lo
	s_cmp_lg_u32 s100, 0
	s_cselect_b32 s100, 1, 0
	v_lshrrev_b32_e32 v32, 6, v200
	v_add_u32_e32 v32, s101, v32
	v_and_b32_e32 v52, 0xffffff00, v32
	v_add_u32_e32 v52, 0x100, v52
	v_cmp_lt_i32_e32 vcc, v32, v52
	s_and_b64 exec, exec, vcc
	s_cbranch_execz .LBB0_393
	v_and_b32_e32 v59, 63, v0
	v_readlane_b32 s40, v254, 61
	v_mov_b64_e32 v[18:19], s[0:1]
	v_lshlrev_b32_e32 v128, 4, v59
	v_readlane_b32 s48, v255, 5
	v_readlane_b32 s49, v255, 6
	v_mad_i64_i32 v[18:19], s[0:1], v16, s84, v[18:19]
	s_nop 3
	global_load_dwordx4 v[0:3], v128, s[48:49]
	global_load_dwordx4 v[4:7], v128, s[48:49] offset:1024
	global_load_dwordx4 v[8:11], v128, s[48:49] offset:2048
	global_load_dwordx4 v[12:15], v128, s[48:49] offset:3072
	v_lshl_add_u64 v[18:19], v[18:19], 0, v[128:129]
	v_readlane_b32 s0, v255, 25
	v_readlane_b32 s1, v255, 26
	global_load_dwordx4 v[38:41], v[18:19], off
	global_load_dwordx4 v[42:45], v[18:19], off offset:1024
	v_mov_b64_e32 v[20:21], s[0:1]
	v_mad_i64_i32 v[16:17], s[0:1], v16, s84, v[20:21]
	v_lshl_add_u64 v[28:29], v[16:17], 0, v[128:129]
	global_load_dwordx4 v[46:49], v[18:19], off offset:2048
	global_load_dwordx4 v[60:63], v[18:19], off offset:3072
	s_nop 0
	global_load_dwordx4 v[16:19], v[28:29], off
	global_load_dwordx4 v[20:23], v[28:29], off offset:1024
	global_load_dwordx4 v[24:27], v[28:29], off offset:2048
	s_nop 0
	global_load_dwordx4 v[28:31], v[28:29], off offset:3072
	v_cmp_lt_i32_e32 vcc, v206, v205
	v_xor_b32_e32 v51, 8, v204
	v_sub_u32_e32 v64, v33, v35
	v_cndmask_b32_e32 v36, v204, v206, vcc
	v_cmp_lt_i32_e32 vcc, v207, v205
	v_lshlrev_b32_e32 v65, 12, v33
	v_ashrrev_i32_e32 v33, 31, v32
	v_cndmask_b32_e32 v37, v204, v207, vcc
	v_cmp_lt_i32_e32 vcc, v252, v205
	v_lshlrev_b32_e32 v35, 12, v35
	v_lshlrev_b32_e32 v53, 2, v36
	v_cndmask_b32_e32 v50, v204, v252, vcc
	v_cmp_lt_i32_e32 vcc, v51, v205
	v_lshlrev_b32_e32 v54, 2, v37
	v_lshlrev_b32_e32 v55, 2, v50
	v_cndmask_b32_e32 v51, v204, v51, vcc
	v_cmp_lt_i32_e32 vcc, v210, v205
	v_lshlrev_b32_e32 v56, 2, v51
	v_mul_lo_u32 v64, v64, s15
	v_cndmask_b32_e32 v57, v204, v210, vcc
	v_cmp_lt_i32_e32 vcc, v211, v205
	v_lshlrev_b64 v[36:37], 11, v[32:33]
	v_lshlrev_b64 v[50:51], 12, v[32:33]
	v_readlane_b32 s12, v255, 13
	v_cndmask_b32_e32 v58, v204, v211, vcc
	s_mov_b32 s7, 0
	s_mov_b32 s6, 32
	v_add3_u32 v32, v34, v64, v35
	v_lshl_or_b32 v36, v59, 3, v36
	v_or_b32_e32 v50, v50, v128
	v_readlane_b32 s13, v255, 14
	v_lshlrev_b32_e32 v57, 2, v57
	v_lshlrev_b32_e32 v58, 2, v58
	s_lshl_b64 s[0:1], s[6:7], 11
	s_lshl_b64 s[6:7], s[6:7], 12
	v_sub_u32_e32 v59, v32, v65
	v_lshrrev_b32_e32 v59, 6, v200
	v_add_u32_e32 v59, s101, v59
	v_lshl_add_u64 v[32:33], s[8:9], 0, v[36:37]
	v_lshl_add_u64 v[34:35], s[12:13], 0, v[50:51]
	s_mov_b64 s[12:13], 0
	v_readlane_b32 s41, v254, 62
	v_readlane_b32 s42, v254, 63
	v_readlane_b32 s43, v255, 0
	v_readlane_b32 s44, v255, 1
	v_readlane_b32 s45, v255, 2
	v_readlane_b32 s46, v255, 3
	v_readlane_b32 s47, v255, 4
	v_readlane_b32 s50, v255, 7
	v_readlane_b32 s51, v255, 8
	v_readlane_b32 s52, v255, 9
	v_readlane_b32 s53, v255, 10
	v_readlane_b32 s54, v255, 11
	v_readlane_b32 s55, v255, 12
	s_waitcnt vmcnt(7)
	v_pk_add_f32 v[36:37], v[40:41], 1.0 op_sel_hi:[1,0]
	v_pk_add_f32 v[38:39], v[38:39], 1.0 op_sel_hi:[1,0]
	s_waitcnt vmcnt(6)
	v_pk_add_f32 v[40:41], v[44:45], 1.0 op_sel_hi:[1,0]
	v_pk_add_f32 v[42:43], v[42:43], 1.0 op_sel_hi:[1,0]
	s_waitcnt vmcnt(5)
	v_pk_add_f32 v[44:45], v[48:49], 1.0 op_sel_hi:[1,0]
	v_pk_add_f32 v[46:47], v[46:47], 1.0 op_sel_hi:[1,0]
	s_waitcnt vmcnt(4)
	v_pk_add_f32 v[48:49], v[62:63], 1.0 op_sel_hi:[1,0]
	v_pk_add_f32 v[50:51], v[60:61], 1.0 op_sel_hi:[1,0]

.Ltb_noreg:
	s_mov_b32 s2, 0xf0f84
	s_bitcmp1_b32 s2, s80
	s_cbranch_scc0 .Ltb_grid
	v_readlane_b32 s3, v255, 47
	s_add_i32 s3, s3, 1
	v_writelane_b32 v255, s3, 47
	s_lshl_b32 s19, s3, 2
	v_readlane_b32 s6, v254, 44
	v_readlane_b32 s7, v254, 45
	s_bfe_u32 s13, s61, 0x60003
	s_and_b32 s14, s13, 7
	s_lshr_b32 s13, s13, 3
	s_lshl_b32 s15, s14, 3
	s_add_u32 s15, s15, s13
	s_lshl_b32 s14, s14, 6
	s_lshl_b32 s13, s13, 2
	s_add_u32 s14, s14, s13
	s_add_u32 s14, s14, 0x300
	s_add_u32 s12, s6, s14
	s_addc_u32 s13, s7, 0
	s_cmp_lg_u32 s80, 2
	s_cbranch_scc1 .Ltb_cached
	s_lshl_b32 s15, s15, 2
	s_add_u32 s15, s15, 0x200
	s_add_u32 s16, s6, s15
	s_addc_u32 s17, s7, 0
	v_readlane_b32 s20, v254, 40
	s_sub_u32 s20, s20, s6
	s_add_u32 s20, s20, 0x2000
	s_lshr_b32 s20, s20, 8
	s_lshl_b32 s20, s20, 2
	s_lshl_b32 s20, 4, s20
	global_load_dword v4, v129, s[16:17] sc1
	s_waitcnt vmcnt(0)
	v_readfirstlane_b32 s21, v4
	s_cmp_eq_u32 s21, s20
	s_cselect_b32 s21, 1, 0
	v_writelane_b32 v255, s21, 45
	s_branch .Ltb_haveflag

.Ltb_done:
	s_cmp_lg_u32 s80, 11
	s_cbranch_scc1 .Ltb_nodep
	v_readlane_b32 s6, v254, 44
	v_readlane_b32 s7, v254, 45
	s_bfe_u32 s13, s61, 0x60003
	s_and_b32 s14, s13, 7
	s_lshr_b32 s13, s13, 3
	s_lshl_b32 s15, s14, 4
	s_add_i32 s15, s15, s13
	s_add_i32 s2, s15, 8
	s_mul_i32 s16, s15, 31
	s_mul_i32 s17, s16, 0xba3
	s_lshr_b32 s17, s17, 16
	s_add_i32 s16, s16, 30
	s_mul_i32 s16, s16, 0xba3
	s_lshr_b32 s16, s16, 16
	s_min_u32 s16, s16, 0x7f
	s_add_i32 s20, s17, 0
	s_cmp_le_u32 s20, s16
	s_cselect_b32 s20, s20, s15
	s_and_b32 s24, s20, 1
	s_lshl_b32 s24, s24, 3
	s_add_i32 s24, s24, 20
	s_lshr_b32 s3, s20, 4
	s_lshl_b32 s3, s3, 6
	s_and_b32 s20, s20, 7
	s_lshl_b32 s20, s20, 2
	s_add_i32 s20, s20, s3
	s_add_i32 s20, s20, 0x300
	v_mov_b32_e32 v5, s20
	s_add_i32 s20, s17, 1
	s_cmp_le_u32 s20, s16
	s_cselect_b32 s20, s20, s15
	s_and_b32 s25, s20, 1
	s_lshl_b32 s25, s25, 3
	s_add_i32 s25, s25, 20
	s_lshr_b32 s3, s20, 4
	s_lshl_b32 s3, s3, 6
	s_and_b32 s20, s20, 7
	s_lshl_b32 s20, s20, 2
	s_add_i32 s20, s20, s3
	s_add_i32 s20, s20, 0x300
	v_mov_b32_e32 v6, s20
	s_add_i32 s20, s17, 2
	s_cmp_le_u32 s20, s16
	s_cselect_b32 s20, s20, s15
	s_and_b32 s12, s20, 1
	s_lshl_b32 s12, s12, 3
	s_add_i32 s12, s12, 20
	s_lshr_b32 s3, s20, 4
	s_lshl_b32 s3, s3, 6
	s_and_b32 s20, s20, 7
	s_lshl_b32 s20, s20, 2
	s_add_i32 s20, s20, s3
	s_add_i32 s20, s20, 0x300
	v_mov_b32_e32 v7, s20
	s_mul_i32 s16, s2, 31
	s_mul_i32 s17, s16, 0xba3
	s_lshr_b32 s17, s17, 16
	s_add_i32 s16, s16, 30
	s_mul_i32 s16, s16, 0xba3
	s_lshr_b32 s16, s16, 16
	s_min_u32 s16, s16, 0x7f
	s_add_i32 s20, s17, 0
	s_cmp_le_u32 s20, s16
	s_cselect_b32 s20, s20, s15
	s_and_b32 s13, s20, 1
	s_lshl_b32 s13, s13, 3
	s_add_i32 s13, s13, 20
	s_lshr_b32 s3, s20, 4
	s_lshl_b32 s3, s3, 6
	s_and_b32 s20, s20, 7
	s_lshl_b32 s20, s20, 2
	s_add_i32 s20, s20, s3
	s_add_i32 s20, s20, 0x300
	v_mov_b32_e32 v8, s20
	s_add_i32 s20, s17, 1
	s_cmp_le_u32 s20, s16
	s_cselect_b32 s20, s20, s15
	s_and_b32 s14, s20, 1
	s_lshl_b32 s14, s14, 3
	s_add_i32 s14, s14, 20
	s_lshr_b32 s3, s20, 4
	s_lshl_b32 s3, s3, 6
	s_and_b32 s20, s20, 7
	s_lshl_b32 s20, s20, 2
	s_add_i32 s20, s20, s3
	s_add_i32 s20, s20, 0x300
	v_mov_b32_e32 v9, s20
	s_add_i32 s20, s17, 2
	s_cmp_le_u32 s20, s16
	s_cselect_b32 s20, s20, s15
	s_and_b32 s19, s20, 1
	s_lshl_b32 s19, s19, 3
	s_add_i32 s19, s19, 20
	s_lshr_b32 s3, s20, 4
	s_lshl_b32 s3, s3, 6
	s_and_b32 s20, s20, 7
	s_lshl_b32 s20, s20, 2
	s_add_i32 s20, s20, s3
	s_add_i32 s20, s20, 0x300
	v_mov_b32_e32 v10, s20
	s_mov_b32 s21, 0
.Ltb_dep:
	global_load_dword v11, v5, s[6:7] sc1
	global_load_dword v12, v6, s[6:7] sc1
	global_load_dword v13, v7, s[6:7] sc1
	global_load_dword v14, v8, s[6:7] sc1
	global_load_dword v15, v9, s[6:7] sc1
	global_load_dword v16, v10, s[6:7] sc1
	s_waitcnt vmcnt(0)
	v_subrev_u32_e32 v11, s24, v11
	v_subrev_u32_e32 v12, s25, v12
	v_subrev_u32_e32 v13, s12, v13
	v_subrev_u32_e32 v14, s13, v14
	v_subrev_u32_e32 v15, s14, v15
	v_subrev_u32_e32 v16, s19, v16
	v_min3_i32 v11, v11, v12, v13
	v_min3_i32 v11, v11, v14, v15
	v_min_i32_e32 v11, v11, v16
	v_readfirstlane_b32 s20, v11
	s_cmp_ge_i32 s20, 0
	s_cbranch_scc1 .Ltb_nodep
	s_add_i32 s21, s21, 1
	s_cmp_lt_u32 s21, 0x2000
	s_cbranch_scc1 .Ltb_dep
